# up-projection conv epilogue: removed the 96 zero-initialising moves in front of full-rotation DPP moves (the rotation writes every lane, the old value is never used)
# baseline (speedup 1.0000x reference)
.LBB0_92:
	s_or_b64 exec, exec, s[10:11]
	s_nop 0
	v_add_f32_e32 v158, v178, v179
	v_add_f32_e32 v159, v180, v181
	v_add_f32_e32 v158, v158, v159
	v_fmamk_f32 v158, v158, 0x3a800000, v254
	v_mov_b32_dpp v160, v170 row_ror:1 row_mask:0xf bank_mask:0xf
	v_mov_b32_dpp v163, v170 row_ror:2 row_mask:0xf bank_mask:0xf
	v_rsq_f32_e32 v158, v158
	v_mov_b32_dpp v161, v166 row_ror:1 row_mask:0xf bank_mask:0xf
	v_mov_b32_dpp v170, v166 row_ror:2 row_mask:0xf bank_mask:0xf
	v_mov_b32_dpp v164, v167 row_ror:1 row_mask:0xf bank_mask:0xf
	v_mov_b32_dpp v178, v167 row_ror:2 row_mask:0xf bank_mask:0xf
	v_mov_b32_dpp v162, v171 row_ror:1 row_mask:0xf bank_mask:0xf
	v_mov_b32_dpp v166, v171 row_ror:2 row_mask:0xf bank_mask:0xf
	v_mov_b32_dpp v167, v168 row_ror:1 row_mask:0xf bank_mask:0xf
	v_mov_b32_dpp v179, v168 row_ror:2 row_mask:0xf bank_mask:0xf
	v_mov_b32_dpp v165, v172 row_ror:1 row_mask:0xf bank_mask:0xf
	v_mov_b32_dpp v171, v172 row_ror:2 row_mask:0xf bank_mask:0xf
	v_mov_b32_dpp v168, v173 row_ror:1 row_mask:0xf bank_mask:0xf
	v_mov_b32_dpp v180, v173 row_ror:2 row_mask:0xf bank_mask:0xf
	v_mov_b32_dpp v172, v169 row_ror:1 row_mask:0xf bank_mask:0xf
	v_pk_mul_f32 v[156:157], v[156:157], v[158:159] op_sel_hi:[1,0]
	v_mov_b32_dpp v173, v169 row_ror:2 row_mask:0xf bank_mask:0xf
	v_add_u32_e32 v169, 16, v183
	v_pk_mul_f32 v[154:155], v[154:155], v[158:159] op_sel_hi:[1,0]
	v_pk_mul_f32 v[152:153], v[152:153], v[158:159] op_sel_hi:[1,0]
	v_pk_mul_f32 v[150:151], v[150:151], v[158:159] op_sel_hi:[1,0]
	v_add_u32_e32 v159, s48, v169
	v_cmp_lt_i32_e64 s[8:9], 1, v169
	v_cmp_gt_i32_e64 s[10:11], s80, v159
	v_mov_b32_dpp v160, v154 row_shr:1 row_mask:0xf bank_mask:0xf
	v_mov_b32_dpp v161, v150 row_shr:1 row_mask:0xf bank_mask:0xf
	v_mov_b32_dpp v163, v154 row_shr:2 row_mask:0xf bank_mask:0xf
	v_mov_b32_dpp v170, v150 row_shr:2 row_mask:0xf bank_mask:0xf
	v_mov_b32_dpp v162, v155 row_shr:1 row_mask:0xf bank_mask:0xf
	v_mov_b32_dpp v164, v151 row_shr:1 row_mask:0xf bank_mask:0xf
	v_mov_b32_dpp v166, v155 row_shr:2 row_mask:0xf bank_mask:0xf
	v_mov_b32_dpp v178, v151 row_shr:2 row_mask:0xf bank_mask:0xf
	v_mov_b32_dpp v165, v156 row_shr:1 row_mask:0xf bank_mask:0xf
	v_mov_b32_dpp v167, v152 row_shr:1 row_mask:0xf bank_mask:0xf
	v_mov_b32_dpp v171, v156 row_shr:2 row_mask:0xf bank_mask:0xf
	v_mov_b32_dpp v179, v152 row_shr:2 row_mask:0xf bank_mask:0xf
	v_mov_b32_dpp v168, v157 row_shr:1 row_mask:0xf bank_mask:0xf
	v_mov_b32_dpp v172, v153 row_shr:1 row_mask:0xf bank_mask:0xf
	v_mov_b32_dpp v180, v157 row_shr:2 row_mask:0xf bank_mask:0xf
	v_mov_b32_dpp v173, v153 row_shr:2 row_mask:0xf bank_mask:0xf
	s_and_b64 s[8:9], s[8:9], s[10:11]
	s_and_saveexec_b64 s[10:11], s[8:9]
	s_cbranch_execz .LBB0_94
	v_and_b32_e32 v169, 0x1fff, v159
	v_cmp_gt_u32_e64 s[8:9], 2, v169
	v_pk_mul_f32 v[146:147], v[146:147], v[158:159] op_sel_hi:[1,0]
	v_pk_mul_f32 v[148:149], v[148:149], v[158:159] op_sel_hi:[1,0]
	v_cndmask_b32_e64 v185, v178, 0, s[8:9]
	v_cndmask_b32_e64 v184, v170, 0, s[8:9]
	v_cndmask_b32_e64 v187, v173, 0, s[8:9]
	v_cndmask_b32_e64 v186, v179, 0, s[8:9]
	v_cndmask_b32_e64 v179, v166, 0, s[8:9]
	v_cndmask_b32_e64 v178, v163, 0, s[8:9]
	v_cndmask_b32_e64 v181, v180, 0, s[8:9]
	v_cndmask_b32_e64 v180, v171, 0, s[8:9]
	v_cmp_eq_u32_e64 s[8:9], 0, v169
	v_pk_mul_f32 v[142:143], v[142:143], v[158:159] op_sel_hi:[1,0]
	v_pk_mul_f32 v[144:145], v[144:145], v[158:159] op_sel_hi:[1,0]
	v_cndmask_b32_e64 v170, v167, 0, s[8:9]
	v_cndmask_b32_e64 v167, v164, 0, s[8:9]
	v_cndmask_b32_e64 v166, v161, 0, s[8:9]
	v_cndmask_b32_e64 v169, v168, 0, s[8:9]
	v_cndmask_b32_e64 v168, v165, 0, s[8:9]
	s_waitcnt vmcnt(1)
	v_pk_fma_f32 v[164:165], v[78:79], v[184:185], v[82:83]
	v_cndmask_b32_e64 v171, v172, 0, s[8:9]
	v_pk_fma_f32 v[164:165], v[74:75], v[166:167], v[164:165]
	v_cndmask_b32_e64 v161, v162, 0, s[8:9]
	v_pk_fma_f32 v[164:165], v[150:151], v[70:71], v[164:165]
	v_pk_fma_f32 v[162:163], v[80:81], v[186:187], v[84:85]
	v_mul_f32_e32 v166, 0xbfb8aa3b, v164
	v_mul_f32_e32 v167, 0xbfb8aa3b, v165
	v_exp_f32_e32 v166, v166
	v_exp_f32_e32 v167, v167
	v_pk_fma_f32 v[162:163], v[76:77], v[170:171], v[162:163]
	v_cndmask_b32_e64 v160, v160, 0, s[8:9]
	v_add_f32_e32 v166, 1.0, v166
	v_add_f32_e32 v167, 1.0, v167
	v_rcp_f32_e32 v166, v166
	v_rcp_f32_e32 v167, v167
	v_pk_fma_f32 v[162:163], v[152:153], v[72:73], v[162:163]
	v_pk_mul_f32 v[164:165], v[164:165], v[166:167]
	s_nop 0
	v_pk_mul_f32 v[146:147], v[146:147], v[164:165]
	v_mul_f32_e32 v164, 0xbfb8aa3b, v162
	v_mul_f32_e32 v165, 0xbfb8aa3b, v163
	v_exp_f32_e32 v164, v164
	v_exp_f32_e32 v165, v165
	v_add_f32_e32 v164, 1.0, v164
	v_add_f32_e32 v165, 1.0, v165
	v_rcp_f32_e32 v164, v164
	v_rcp_f32_e32 v165, v165
	s_nop 0
	v_pk_mul_f32 v[162:163], v[162:163], v[164:165]
	s_waitcnt vmcnt(0)
	v_pk_fma_f32 v[164:165], v[50:51], v[178:179], v[58:59]
	v_pk_mul_f32 v[148:149], v[148:149], v[162:163]
	v_pk_fma_f32 v[160:161], v[46:47], v[160:161], v[164:165]
	v_pk_fma_f32 v[162:163], v[52:53], v[180:181], v[60:61]
	v_pk_fma_f32 v[160:161], v[154:155], v[42:43], v[160:161]
	v_pk_fma_f32 v[162:163], v[48:49], v[168:169], v[162:163]
	v_mul_f32_e32 v164, 0xbfb8aa3b, v160
	v_mul_f32_e32 v165, 0xbfb8aa3b, v161
	v_exp_f32_e32 v164, v164
	v_exp_f32_e32 v165, v165
	v_pk_fma_f32 v[162:163], v[156:157], v[44:45], v[162:163]
	v_add_f32_e32 v164, 1.0, v164
	v_add_f32_e32 v165, 1.0, v165
	v_rcp_f32_e32 v164, v164
	v_rcp_f32_e32 v165, v165
	s_nop 0
	v_pk_mul_f32 v[160:161], v[160:161], v[164:165]
	s_nop 0
	v_pk_mul_f32 v[142:143], v[142:143], v[160:161]
	v_mul_f32_e32 v160, 0xbfb8aa3b, v162
	v_mul_f32_e32 v161, 0xbfb8aa3b, v163
	v_exp_f32_e32 v160, v160
	v_exp_f32_e32 v161, v161
	v_cvt_pk_bf16_f32 v142, v142, v143
	v_add_f32_e32 v160, 1.0, v160
	v_add_f32_e32 v161, 1.0, v161
	v_rcp_f32_e32 v160, v160
	v_rcp_f32_e32 v161, v161
	s_nop 0
	v_pk_mul_f32 v[160:161], v[162:163], v[160:161]
	s_nop 0
	v_pk_mul_f32 v[144:145], v[144:145], v[160:161]
	s_nop 0
	v_cvt_pk_bf16_f32 v143, v144, v145
	v_cvt_pk_bf16_f32 v144, v146, v147
	v_mov_b64_e32 v[146:147], s[16:17]
	v_mad_i64_i32 v[146:147], s[8:9], v159, s58, v[146:147]
	v_cvt_pk_bf16_f32 v145, v148, v149
	v_lshl_add_u64 v[146:147], v[226:227], 1, v[146:147]
	global_store_dwordx4 v[146:147], v[142:145], off
.LBB0_94:
	s_or_b64 exec, exec, s[10:11]
	s_nop 0
	v_add_f32_e32 v142, v174, v175
	v_add_f32_e32 v143, v176, v177
	v_add_f32_e32 v142, v142, v143
	v_fmamk_f32 v142, v142, 0x3a800000, v254
	v_mov_b32_dpp v144, v154 row_ror:1 row_mask:0xf bank_mask:0xf
	v_mov_b32_dpp v147, v154 row_ror:2 row_mask:0xf bank_mask:0xf
	v_rsq_f32_e32 v142, v142
	v_mov_b32_dpp v145, v150 row_ror:1 row_mask:0xf bank_mask:0xf
	v_mov_b32_dpp v154, v150 row_ror:2 row_mask:0xf bank_mask:0xf
	v_mov_b32_dpp v148, v151 row_ror:1 row_mask:0xf bank_mask:0xf
	v_mov_b32_dpp v158, v151 row_ror:2 row_mask:0xf bank_mask:0xf
	v_mov_b32_dpp v146, v155 row_ror:1 row_mask:0xf bank_mask:0xf
	v_mov_b32_dpp v150, v155 row_ror:2 row_mask:0xf bank_mask:0xf
	v_mov_b32_dpp v151, v152 row_ror:1 row_mask:0xf bank_mask:0xf
	v_mov_b32_dpp v159, v152 row_ror:2 row_mask:0xf bank_mask:0xf
	v_mov_b32_dpp v149, v156 row_ror:1 row_mask:0xf bank_mask:0xf
	v_mov_b32_dpp v155, v156 row_ror:2 row_mask:0xf bank_mask:0xf
	v_mov_b32_dpp v152, v157 row_ror:1 row_mask:0xf bank_mask:0xf
	v_mov_b32_dpp v160, v157 row_ror:2 row_mask:0xf bank_mask:0xf
	v_mov_b32_dpp v156, v153 row_ror:1 row_mask:0xf bank_mask:0xf
	v_pk_mul_f32 v[140:141], v[140:141], v[142:143] op_sel_hi:[1,0]
	v_mov_b32_dpp v157, v153 row_ror:2 row_mask:0xf bank_mask:0xf
	v_add_u32_e32 v153, 32, v183
	v_pk_mul_f32 v[138:139], v[138:139], v[142:143] op_sel_hi:[1,0]
	v_pk_mul_f32 v[132:133], v[132:133], v[142:143] op_sel_hi:[1,0]
	v_pk_mul_f32 v[130:131], v[130:131], v[142:143] op_sel_hi:[1,0]
	v_add_u32_e32 v143, s48, v153
	v_cmp_lt_i32_e64 s[8:9], 1, v153
	v_cmp_gt_i32_e64 s[10:11], s80, v143
	v_mov_b32_dpp v144, v138 row_shr:1 row_mask:0xf bank_mask:0xf
	v_mov_b32_dpp v145, v130 row_shr:1 row_mask:0xf bank_mask:0xf
	v_mov_b32_dpp v147, v138 row_shr:2 row_mask:0xf bank_mask:0xf
	v_mov_b32_dpp v154, v130 row_shr:2 row_mask:0xf bank_mask:0xf
	v_mov_b32_dpp v146, v139 row_shr:1 row_mask:0xf bank_mask:0xf
	v_mov_b32_dpp v148, v131 row_shr:1 row_mask:0xf bank_mask:0xf
	v_mov_b32_dpp v150, v139 row_shr:2 row_mask:0xf bank_mask:0xf
	v_mov_b32_dpp v158, v131 row_shr:2 row_mask:0xf bank_mask:0xf
	v_mov_b32_dpp v149, v140 row_shr:1 row_mask:0xf bank_mask:0xf
	v_mov_b32_dpp v151, v132 row_shr:1 row_mask:0xf bank_mask:0xf
	v_mov_b32_dpp v155, v140 row_shr:2 row_mask:0xf bank_mask:0xf
	v_mov_b32_dpp v159, v132 row_shr:2 row_mask:0xf bank_mask:0xf
	v_mov_b32_dpp v152, v141 row_shr:1 row_mask:0xf bank_mask:0xf
	v_mov_b32_dpp v156, v133 row_shr:1 row_mask:0xf bank_mask:0xf
	v_mov_b32_dpp v160, v141 row_shr:2 row_mask:0xf bank_mask:0xf
	v_mov_b32_dpp v157, v133 row_shr:2 row_mask:0xf bank_mask:0xf
	s_and_b64 s[8:9], s[8:9], s[10:11]
	s_and_saveexec_b64 s[10:11], s[8:9]
	s_cbranch_execz .LBB0_96
	v_and_b32_e32 v153, 0x1fff, v143
	v_cmp_gt_u32_e64 s[8:9], 2, v153
	v_pk_mul_f32 v[126:127], v[126:127], v[142:143] op_sel_hi:[1,0]
	v_pk_mul_f32 v[128:129], v[128:129], v[142:143] op_sel_hi:[1,0]
	v_cndmask_b32_e64 v163, v158, 0, s[8:9]
	v_cndmask_b32_e64 v162, v154, 0, s[8:9]
	v_cndmask_b32_e64 v165, v157, 0, s[8:9]
	v_cndmask_b32_e64 v164, v159, 0, s[8:9]
	v_cndmask_b32_e64 v159, v150, 0, s[8:9]
	v_cndmask_b32_e64 v158, v147, 0, s[8:9]
	v_cndmask_b32_e64 v161, v160, 0, s[8:9]
	v_cndmask_b32_e64 v160, v155, 0, s[8:9]
	v_cmp_eq_u32_e64 s[8:9], 0, v153
	v_pk_mul_f32 v[114:115], v[114:115], v[142:143] op_sel_hi:[1,0]
	v_pk_mul_f32 v[116:117], v[116:117], v[142:143] op_sel_hi:[1,0]
	v_cndmask_b32_e64 v154, v151, 0, s[8:9]
	v_cndmask_b32_e64 v151, v148, 0, s[8:9]
	v_cndmask_b32_e64 v150, v145, 0, s[8:9]
	v_cndmask_b32_e64 v153, v152, 0, s[8:9]
	v_cndmask_b32_e64 v152, v149, 0, s[8:9]
	s_waitcnt vmcnt(1)
	v_pk_fma_f32 v[148:149], v[78:79], v[162:163], v[82:83]
	v_cndmask_b32_e64 v155, v156, 0, s[8:9]
	v_pk_fma_f32 v[148:149], v[74:75], v[150:151], v[148:149]
	v_cndmask_b32_e64 v145, v146, 0, s[8:9]
	v_pk_fma_f32 v[148:149], v[130:131], v[70:71], v[148:149]
	v_pk_fma_f32 v[146:147], v[80:81], v[164:165], v[84:85]
	v_mul_f32_e32 v150, 0xbfb8aa3b, v148
	v_mul_f32_e32 v151, 0xbfb8aa3b, v149
	v_exp_f32_e32 v150, v150
	v_exp_f32_e32 v151, v151
	v_pk_fma_f32 v[146:147], v[76:77], v[154:155], v[146:147]
	v_cndmask_b32_e64 v144, v144, 0, s[8:9]
	v_add_f32_e32 v150, 1.0, v150
	v_add_f32_e32 v151, 1.0, v151
	v_rcp_f32_e32 v150, v150
	v_rcp_f32_e32 v151, v151
	v_pk_fma_f32 v[146:147], v[132:133], v[72:73], v[146:147]
	v_pk_mul_f32 v[148:149], v[148:149], v[150:151]
	s_nop 0
	v_pk_mul_f32 v[126:127], v[126:127], v[148:149]
	v_mul_f32_e32 v148, 0xbfb8aa3b, v146
	v_mul_f32_e32 v149, 0xbfb8aa3b, v147
	v_exp_f32_e32 v148, v148
	v_exp_f32_e32 v149, v149
	v_add_f32_e32 v148, 1.0, v148
	v_add_f32_e32 v149, 1.0, v149
	v_rcp_f32_e32 v148, v148
	v_rcp_f32_e32 v149, v149
	s_nop 0
	v_pk_mul_f32 v[146:147], v[146:147], v[148:149]
	s_waitcnt vmcnt(0)
	v_pk_fma_f32 v[148:149], v[50:51], v[158:159], v[58:59]
	v_pk_mul_f32 v[128:129], v[128:129], v[146:147]
	v_pk_fma_f32 v[144:145], v[46:47], v[144:145], v[148:149]
	v_pk_fma_f32 v[146:147], v[52:53], v[160:161], v[60:61]
	v_pk_fma_f32 v[144:145], v[138:139], v[42:43], v[144:145]
	v_pk_fma_f32 v[146:147], v[48:49], v[152:153], v[146:147]
	v_mul_f32_e32 v148, 0xbfb8aa3b, v144
	v_mul_f32_e32 v149, 0xbfb8aa3b, v145
	v_exp_f32_e32 v148, v148
	v_exp_f32_e32 v149, v149
	v_pk_fma_f32 v[146:147], v[140:141], v[44:45], v[146:147]
	v_add_f32_e32 v148, 1.0, v148
	v_add_f32_e32 v149, 1.0, v149
	v_rcp_f32_e32 v148, v148
	v_rcp_f32_e32 v149, v149
	s_nop 0
	v_pk_mul_f32 v[144:145], v[144:145], v[148:149]
	s_nop 0
	v_pk_mul_f32 v[114:115], v[114:115], v[144:145]
	v_mul_f32_e32 v144, 0xbfb8aa3b, v146
	v_mul_f32_e32 v145, 0xbfb8aa3b, v147
	v_exp_f32_e32 v144, v144
	v_exp_f32_e32 v145, v145
	v_cvt_pk_bf16_f32 v114, v114, v115
	v_add_f32_e32 v144, 1.0, v144
	v_add_f32_e32 v145, 1.0, v145
	v_rcp_f32_e32 v144, v144
	v_rcp_f32_e32 v145, v145
	s_nop 0
	v_pk_mul_f32 v[144:145], v[146:147], v[144:145]
	s_nop 0
	v_pk_mul_f32 v[116:117], v[116:117], v[144:145]
	s_nop 0
	v_cvt_pk_bf16_f32 v115, v116, v117
	v_cvt_pk_bf16_f32 v116, v126, v127
	v_mov_b64_e32 v[126:127], s[16:17]
	v_mad_i64_i32 v[126:127], s[8:9], v143, s58, v[126:127]
	v_cvt_pk_bf16_f32 v117, v128, v129
	v_lshl_add_u64 v[126:127], v[226:227], 1, v[126:127]
	global_store_dwordx4 v[126:127], v[114:117], off
.LBB0_96:
	s_or_b64 exec, exec, s[10:11]
	s_nop 0
	v_pk_mul_f32 v[114:115], v[120:121], v[228:229] op_sel_hi:[1,0]
	v_mov_b32_dpp v120, v130 row_ror:1 row_mask:0xf bank_mask:0xf
	v_mov_b32_dpp v129, v130 row_ror:2 row_mask:0xf bank_mask:0xf
	v_mov_b32_dpp v121, v139 row_ror:1 row_mask:0xf bank_mask:0xf
	v_mov_b32_dpp v130, v139 row_ror:2 row_mask:0xf bank_mask:0xf
	v_pk_mul_f32 v[116:117], v[118:119], v[228:229] op_sel_hi:[1,0]
	v_mov_b32_dpp v127, v131 row_ror:1 row_mask:0xf bank_mask:0xf
	v_mov_b32_dpp v139, v131 row_ror:2 row_mask:0xf bank_mask:0xf
	v_mov_b32_dpp v119, v138 row_ror:1 row_mask:0xf bank_mask:0xf
	v_mov_b32_dpp v126, v138 row_ror:2 row_mask:0xf bank_mask:0xf
	v_mov_b32_dpp v131, v132 row_ror:1 row_mask:0xf bank_mask:0xf
	v_mov_b32_dpp v142, v132 row_ror:2 row_mask:0xf bank_mask:0xf
	v_mov_b32_dpp v128, v140 row_ror:1 row_mask:0xf bank_mask:0xf
	v_mov_b32_dpp v138, v140 row_ror:2 row_mask:0xf bank_mask:0xf
	v_mov_b32_dpp v132, v141 row_ror:1 row_mask:0xf bank_mask:0xf
	v_mov_b32_dpp v143, v141 row_ror:2 row_mask:0xf bank_mask:0xf
	v_mov_b32_dpp v140, v133 row_ror:1 row_mask:0xf bank_mask:0xf
	v_pk_mul_f32 v[112:113], v[112:113], v[228:229] op_sel_hi:[1,0]
	v_mov_b32_dpp v141, v133 row_ror:2 row_mask:0xf bank_mask:0xf
	v_add_u32_e32 v133, 48, v183
	v_add_u32_e32 v118, s48, v133
	v_pk_mul_f32 v[110:111], v[110:111], v[228:229] op_sel_hi:[1,0]
	v_cmp_lt_i32_e64 s[8:9], 1, v133
	v_cmp_gt_i32_e64 s[10:11], s80, v118
	v_mov_b32_dpp v119, v116 row_shr:1 row_mask:0xf bank_mask:0xf
	v_mov_b32_dpp v120, v110 row_shr:1 row_mask:0xf bank_mask:0xf
	v_mov_b32_dpp v126, v116 row_shr:2 row_mask:0xf bank_mask:0xf
	v_mov_b32_dpp v129, v110 row_shr:2 row_mask:0xf bank_mask:0xf
	v_mov_b32_dpp v121, v117 row_shr:1 row_mask:0xf bank_mask:0xf
	v_mov_b32_dpp v127, v111 row_shr:1 row_mask:0xf bank_mask:0xf
	v_mov_b32_dpp v130, v117 row_shr:2 row_mask:0xf bank_mask:0xf
	v_mov_b32_dpp v139, v111 row_shr:2 row_mask:0xf bank_mask:0xf
	v_mov_b32_dpp v128, v114 row_shr:1 row_mask:0xf bank_mask:0xf
	v_mov_b32_dpp v131, v112 row_shr:1 row_mask:0xf bank_mask:0xf
	v_mov_b32_dpp v138, v114 row_shr:2 row_mask:0xf bank_mask:0xf
	v_mov_b32_dpp v142, v112 row_shr:2 row_mask:0xf bank_mask:0xf
	v_mov_b32_dpp v132, v115 row_shr:1 row_mask:0xf bank_mask:0xf
	v_mov_b32_dpp v140, v113 row_shr:1 row_mask:0xf bank_mask:0xf
	v_mov_b32_dpp v143, v115 row_shr:2 row_mask:0xf bank_mask:0xf
	v_mov_b32_dpp v141, v113 row_shr:2 row_mask:0xf bank_mask:0xf
	s_and_b64 s[8:9], s[8:9], s[10:11]
	s_and_saveexec_b64 s[10:11], s[8:9]
	s_cbranch_execz .LBB0_98
	v_and_b32_e32 v133, 0x1fff, v118
	v_cmp_gt_u32_e64 s[8:9], 2, v133
	v_pk_mul_f32 v[106:107], v[106:107], v[228:229] op_sel_hi:[1,0]
	v_pk_mul_f32 v[108:109], v[108:109], v[228:229] op_sel_hi:[1,0]
	v_cndmask_b32_e64 v145, v139, 0, s[8:9]
	v_cndmask_b32_e64 v144, v129, 0, s[8:9]
	v_cndmask_b32_e64 v147, v141, 0, s[8:9]
	v_cndmask_b32_e64 v146, v142, 0, s[8:9]
	v_cndmask_b32_e64 v149, v130, 0, s[8:9]
	v_cndmask_b32_e64 v148, v126, 0, s[8:9]
	v_cndmask_b32_e64 v139, v143, 0, s[8:9]
	v_cndmask_b32_e64 v138, v138, 0, s[8:9]
	v_cmp_eq_u32_e64 s[8:9], 0, v133
	v_pk_mul_f32 v[102:103], v[102:103], v[228:229] op_sel_hi:[1,0]
	v_pk_mul_f32 v[104:105], v[104:105], v[228:229] op_sel_hi:[1,0]
	v_cndmask_b32_e64 v127, v127, 0, s[8:9]
	v_cndmask_b32_e64 v126, v120, 0, s[8:9]
	v_cndmask_b32_e64 v129, v132, 0, s[8:9]
	s_waitcnt vmcnt(1)
	v_pk_fma_f32 v[132:133], v[78:79], v[144:145], v[82:83]
	v_cndmask_b32_e64 v120, v119, 0, s[8:9]
	v_pk_fma_f32 v[126:127], v[74:75], v[126:127], v[132:133]
	v_cndmask_b32_e64 v141, v140, 0, s[8:9]
	v_pk_fma_f32 v[110:111], v[110:111], v[70:71], v[126:127]
	v_cndmask_b32_e64 v140, v131, 0, s[8:9]
	v_mul_f32_e32 v119, 0xbfb8aa3b, v110
	v_exp_f32_e32 v119, v119
	v_mul_f32_e32 v126, 0xbfb8aa3b, v111
	v_exp_f32_e32 v127, v126
	v_pk_fma_f32 v[130:131], v[80:81], v[146:147], v[84:85]
	v_add_f32_e32 v119, 1.0, v119
	v_pk_fma_f32 v[130:131], v[76:77], v[140:141], v[130:131]
	v_rcp_f32_e32 v126, v119
	v_pk_fma_f32 v[112:113], v[112:113], v[72:73], v[130:131]
	v_add_f32_e32 v119, 1.0, v127
	v_rcp_f32_e32 v127, v119
	v_mul_f32_e32 v119, 0xbfb8aa3b, v112
	v_exp_f32_e32 v119, v119
	v_mul_f32_e32 v130, 0xbfb8aa3b, v113
	v_exp_f32_e32 v131, v130
	v_pk_mul_f32 v[110:111], v[110:111], v[126:127]
	v_add_f32_e32 v119, 1.0, v119
	v_rcp_f32_e32 v130, v119
	v_add_f32_e32 v119, 1.0, v131
	v_rcp_f32_e32 v131, v119
	v_cndmask_b32_e64 v121, v121, 0, s[8:9]
	v_pk_mul_f32 v[106:107], v[106:107], v[110:111]
	v_cndmask_b32_e64 v128, v128, 0, s[8:9]
	v_pk_mul_f32 v[110:111], v[112:113], v[130:131]
	s_waitcnt vmcnt(0)
	v_pk_fma_f32 v[112:113], v[50:51], v[148:149], v[58:59]
	v_pk_mul_f32 v[108:109], v[108:109], v[110:111]
	v_pk_fma_f32 v[112:113], v[46:47], v[120:121], v[112:113]
	v_pk_fma_f32 v[110:111], v[52:53], v[138:139], v[60:61]
	v_pk_fma_f32 v[112:113], v[116:117], v[42:43], v[112:113]
	v_pk_fma_f32 v[110:111], v[48:49], v[128:129], v[110:111]
	v_mul_f32_e32 v116, 0xbfb8aa3b, v112
	v_mul_f32_e32 v117, 0xbfb8aa3b, v113
	v_exp_f32_e32 v116, v116
	v_exp_f32_e32 v117, v117
	v_pk_fma_f32 v[110:111], v[114:115], v[44:45], v[110:111]
	v_add_f32_e32 v114, 1.0, v116
	v_add_f32_e32 v115, 1.0, v117
	v_mul_f32_e32 v116, 0xbfb8aa3b, v110
	v_mul_f32_e32 v117, 0xbfb8aa3b, v111
	v_exp_f32_e32 v116, v116
	v_exp_f32_e32 v117, v117
	v_rcp_f32_e32 v114, v114
	v_rcp_f32_e32 v115, v115
	v_add_f32_e32 v116, 1.0, v116
	v_add_f32_e32 v117, 1.0, v117
	v_rcp_f32_e32 v116, v116
	v_rcp_f32_e32 v117, v117
	v_pk_mul_f32 v[112:113], v[112:113], v[114:115]
	v_pk_mul_f32 v[110:111], v[110:111], v[116:117]
	v_pk_mul_f32 v[102:103], v[102:103], v[112:113]
	v_pk_mul_f32 v[104:105], v[104:105], v[110:111]
	v_cvt_pk_bf16_f32 v102, v102, v103
	v_cvt_pk_bf16_f32 v103, v104, v105
	v_cvt_pk_bf16_f32 v104, v106, v107
	v_mov_b64_e32 v[106:107], s[16:17]
	v_mad_i64_i32 v[106:107], s[8:9], v118, s58, v[106:107]
	v_cvt_pk_bf16_f32 v105, v108, v109
	v_lshl_add_u64 v[106:107], v[226:227], 1, v[106:107]
	global_store_dwordx4 v[106:107], v[102:105], off

.LBB0_104:
	s_or_b64 exec, exec, s[6:7]
	s_nop 0
	v_add_f32_e32 v66, v122, v123
	v_add_f32_e32 v67, v124, v125
	v_add_f32_e32 v66, v66, v67
	v_fmamk_f32 v66, v66, 0x3a800000, v254
	v_mov_b32_dpp v68, v94 row_ror:1 row_mask:0xf bank_mask:0xf
	v_mov_b32_dpp v87, v94 row_ror:2 row_mask:0xf bank_mask:0xf
	v_rsq_f32_e32 v66, v66
	v_mov_b32_dpp v69, v90 row_ror:1 row_mask:0xf bank_mask:0xf
	v_mov_b32_dpp v94, v90 row_ror:2 row_mask:0xf bank_mask:0xf
	v_mov_b32_dpp v88, v91 row_ror:1 row_mask:0xf bank_mask:0xf
	v_mov_b32_dpp v102, v91 row_ror:2 row_mask:0xf bank_mask:0xf
	v_mov_b32_dpp v86, v95 row_ror:1 row_mask:0xf bank_mask:0xf
	v_mov_b32_dpp v90, v95 row_ror:2 row_mask:0xf bank_mask:0xf
	v_mov_b32_dpp v91, v92 row_ror:1 row_mask:0xf bank_mask:0xf
	v_mov_b32_dpp v103, v92 row_ror:2 row_mask:0xf bank_mask:0xf
	v_mov_b32_dpp v89, v96 row_ror:1 row_mask:0xf bank_mask:0xf
	v_mov_b32_dpp v95, v96 row_ror:2 row_mask:0xf bank_mask:0xf
	v_mov_b32_dpp v92, v97 row_ror:1 row_mask:0xf bank_mask:0xf
	v_mov_b32_dpp v104, v97 row_ror:2 row_mask:0xf bank_mask:0xf
	v_mov_b32_dpp v96, v93 row_ror:1 row_mask:0xf bank_mask:0xf
	v_pk_mul_f32 v[64:65], v[64:65], v[66:67] op_sel_hi:[1,0]
	v_mov_b32_dpp v97, v93 row_ror:2 row_mask:0xf bank_mask:0xf
	v_add_u32_e32 v93, 0x90, v183
	v_pk_mul_f32 v[62:63], v[62:63], v[66:67] op_sel_hi:[1,0]
	v_pk_mul_f32 v[56:57], v[56:57], v[66:67] op_sel_hi:[1,0]
	v_pk_mul_f32 v[54:55], v[54:55], v[66:67] op_sel_hi:[1,0]
	v_add_u32_e32 v67, s48, v93
	v_cmp_lt_i32_e32 vcc, 1, v93
	v_cmp_gt_i32_e64 s[6:7], s80, v67
	v_mov_b32_dpp v68, v62 row_shr:1 row_mask:0xf bank_mask:0xf
	v_mov_b32_dpp v69, v54 row_shr:1 row_mask:0xf bank_mask:0xf
	v_mov_b32_dpp v87, v62 row_shr:2 row_mask:0xf bank_mask:0xf
	v_mov_b32_dpp v94, v54 row_shr:2 row_mask:0xf bank_mask:0xf
	v_mov_b32_dpp v86, v63 row_shr:1 row_mask:0xf bank_mask:0xf
	v_mov_b32_dpp v88, v55 row_shr:1 row_mask:0xf bank_mask:0xf
	v_mov_b32_dpp v90, v63 row_shr:2 row_mask:0xf bank_mask:0xf
	v_mov_b32_dpp v102, v55 row_shr:2 row_mask:0xf bank_mask:0xf
	v_mov_b32_dpp v89, v64 row_shr:1 row_mask:0xf bank_mask:0xf
	v_mov_b32_dpp v91, v56 row_shr:1 row_mask:0xf bank_mask:0xf
	v_mov_b32_dpp v95, v64 row_shr:2 row_mask:0xf bank_mask:0xf
	v_mov_b32_dpp v103, v56 row_shr:2 row_mask:0xf bank_mask:0xf
	v_mov_b32_dpp v92, v65 row_shr:1 row_mask:0xf bank_mask:0xf
	v_mov_b32_dpp v96, v57 row_shr:1 row_mask:0xf bank_mask:0xf
	v_mov_b32_dpp v104, v65 row_shr:2 row_mask:0xf bank_mask:0xf
	v_mov_b32_dpp v97, v57 row_shr:2 row_mask:0xf bank_mask:0xf
	s_and_b64 s[8:9], vcc, s[6:7]
	s_and_saveexec_b64 s[6:7], s[8:9]
	s_cbranch_execz .LBB0_106
	v_and_b32_e32 v93, 0x1fff, v67
	v_cmp_gt_u32_e32 vcc, 2, v93
	v_pk_mul_f32 v[38:39], v[38:39], v[66:67] op_sel_hi:[1,0]
	v_pk_mul_f32 v[40:41], v[40:41], v[66:67] op_sel_hi:[1,0]
	v_cndmask_b32_e64 v107, v102, 0, vcc
	v_cndmask_b32_e64 v106, v94, 0, vcc
	v_cndmask_b32_e64 v109, v97, 0, vcc
	v_cndmask_b32_e64 v108, v103, 0, vcc
	v_cndmask_b32_e64 v103, v90, 0, vcc
	v_cndmask_b32_e64 v102, v87, 0, vcc
	v_cndmask_b32_e64 v105, v104, 0, vcc
	v_cndmask_b32_e64 v104, v95, 0, vcc
	v_cmp_eq_u32_e32 vcc, 0, v93
	v_pk_mul_f32 v[34:35], v[34:35], v[66:67] op_sel_hi:[1,0]
	v_pk_mul_f32 v[36:37], v[36:37], v[66:67] op_sel_hi:[1,0]
	v_cndmask_b32_e64 v94, v91, 0, vcc
	v_cndmask_b32_e64 v91, v88, 0, vcc
	v_cndmask_b32_e64 v90, v69, 0, vcc
	v_cndmask_b32_e64 v93, v92, 0, vcc
	v_cndmask_b32_e64 v92, v89, 0, vcc
	s_waitcnt vmcnt(1)
	v_pk_fma_f32 v[88:89], v[78:79], v[106:107], v[82:83]
	v_cndmask_b32_e64 v95, v96, 0, vcc
	v_pk_fma_f32 v[88:89], v[74:75], v[90:91], v[88:89]
	v_cndmask_b32_e64 v69, v86, 0, vcc
	v_pk_fma_f32 v[88:89], v[54:55], v[70:71], v[88:89]
	v_pk_fma_f32 v[86:87], v[80:81], v[108:109], v[84:85]
	v_mul_f32_e32 v90, 0xbfb8aa3b, v88
	v_mul_f32_e32 v91, 0xbfb8aa3b, v89
	v_exp_f32_e32 v90, v90
	v_exp_f32_e32 v91, v91
	v_pk_fma_f32 v[86:87], v[76:77], v[94:95], v[86:87]
	v_cndmask_b32_e64 v68, v68, 0, vcc
	v_add_f32_e32 v90, 1.0, v90
	v_add_f32_e32 v91, 1.0, v91
	v_rcp_f32_e32 v90, v90
	v_rcp_f32_e32 v91, v91
	v_pk_fma_f32 v[86:87], v[56:57], v[72:73], v[86:87]
	v_pk_mul_f32 v[88:89], v[88:89], v[90:91]
	s_nop 0
	v_pk_mul_f32 v[38:39], v[38:39], v[88:89]
	v_mul_f32_e32 v88, 0xbfb8aa3b, v86
	v_mul_f32_e32 v89, 0xbfb8aa3b, v87
	v_exp_f32_e32 v88, v88
	v_exp_f32_e32 v89, v89
	v_add_f32_e32 v88, 1.0, v88
	v_add_f32_e32 v89, 1.0, v89
	v_rcp_f32_e32 v88, v88
	v_rcp_f32_e32 v89, v89
	s_nop 0
	v_pk_mul_f32 v[86:87], v[86:87], v[88:89]
	s_waitcnt vmcnt(0)
	v_pk_fma_f32 v[88:89], v[50:51], v[102:103], v[58:59]
	v_pk_mul_f32 v[40:41], v[40:41], v[86:87]
	v_pk_fma_f32 v[68:69], v[46:47], v[68:69], v[88:89]
	v_pk_fma_f32 v[86:87], v[52:53], v[104:105], v[60:61]
	v_pk_fma_f32 v[68:69], v[62:63], v[42:43], v[68:69]
	v_pk_fma_f32 v[86:87], v[48:49], v[92:93], v[86:87]
	v_mul_f32_e32 v88, 0xbfb8aa3b, v68
	v_mul_f32_e32 v89, 0xbfb8aa3b, v69
	v_exp_f32_e32 v88, v88
	v_exp_f32_e32 v89, v89
	v_pk_fma_f32 v[86:87], v[64:65], v[44:45], v[86:87]
	v_add_f32_e32 v88, 1.0, v88
	v_add_f32_e32 v89, 1.0, v89
	v_rcp_f32_e32 v88, v88
	v_rcp_f32_e32 v89, v89
	s_nop 0
	v_pk_mul_f32 v[68:69], v[68:69], v[88:89]
	s_nop 0
	v_pk_mul_f32 v[34:35], v[34:35], v[68:69]
	v_mul_f32_e32 v68, 0xbfb8aa3b, v86
	v_mul_f32_e32 v69, 0xbfb8aa3b, v87
	v_exp_f32_e32 v68, v68
	v_exp_f32_e32 v69, v69
	v_cvt_pk_bf16_f32 v34, v34, v35
	v_add_f32_e32 v68, 1.0, v68
	v_add_f32_e32 v69, 1.0, v69
	v_rcp_f32_e32 v68, v68
	v_rcp_f32_e32 v69, v69
	s_nop 0
	v_pk_mul_f32 v[68:69], v[86:87], v[68:69]
	s_nop 0
	v_pk_mul_f32 v[36:37], v[36:37], v[68:69]
	s_nop 0
	v_cvt_pk_bf16_f32 v35, v36, v37
	v_cvt_pk_bf16_f32 v36, v38, v39
	v_mov_b64_e32 v[38:39], s[16:17]
	v_mad_i64_i32 v[38:39], s[8:9], v67, s58, v[38:39]
	v_cvt_pk_bf16_f32 v37, v40, v41
	v_lshl_add_u64 v[38:39], v[226:227], 1, v[38:39]
	global_store_dwordx4 v[38:39], v[34:37], off
.LBB0_106:
	s_or_b64 exec, exec, s[6:7]
	s_nop 0
	v_add_f32_e32 v34, v98, v99
	v_add_f32_e32 v35, v100, v101
	v_add_f32_e32 v34, v34, v35
	v_fmamk_f32 v34, v34, 0x3a800000, v254
	v_mov_b32_dpp v36, v62 row_ror:1 row_mask:0xf bank_mask:0xf
	v_mov_b32_dpp v39, v62 row_ror:2 row_mask:0xf bank_mask:0xf
	v_rsq_f32_e32 v34, v34
	v_mov_b32_dpp v37, v54 row_ror:1 row_mask:0xf bank_mask:0xf
	v_mov_b32_dpp v62, v54 row_ror:2 row_mask:0xf bank_mask:0xf
	v_mov_b32_dpp v40, v55 row_ror:1 row_mask:0xf bank_mask:0xf
	v_mov_b32_dpp v66, v55 row_ror:2 row_mask:0xf bank_mask:0xf
	v_mov_b32_dpp v38, v63 row_ror:1 row_mask:0xf bank_mask:0xf
	v_mov_b32_dpp v54, v63 row_ror:2 row_mask:0xf bank_mask:0xf
	v_mov_b32_dpp v55, v56 row_ror:1 row_mask:0xf bank_mask:0xf
	v_mov_b32_dpp v67, v56 row_ror:2 row_mask:0xf bank_mask:0xf
	v_mov_b32_dpp v41, v64 row_ror:1 row_mask:0xf bank_mask:0xf
	v_mov_b32_dpp v63, v64 row_ror:2 row_mask:0xf bank_mask:0xf
	v_mov_b32_dpp v56, v65 row_ror:1 row_mask:0xf bank_mask:0xf
	v_mov_b32_dpp v68, v65 row_ror:2 row_mask:0xf bank_mask:0xf
	v_mov_b32_dpp v64, v57 row_ror:1 row_mask:0xf bank_mask:0xf
	v_pk_mul_f32 v[32:33], v[32:33], v[34:35] op_sel_hi:[1,0]
	v_mov_b32_dpp v65, v57 row_ror:2 row_mask:0xf bank_mask:0xf
	v_add_u32_e32 v57, 0xa0, v183
	v_pk_mul_f32 v[30:31], v[30:31], v[34:35] op_sel_hi:[1,0]
	v_pk_mul_f32 v[28:29], v[28:29], v[34:35] op_sel_hi:[1,0]
	v_pk_mul_f32 v[26:27], v[26:27], v[34:35] op_sel_hi:[1,0]
	v_add_u32_e32 v35, s48, v57
	v_cmp_lt_i32_e32 vcc, 1, v57
	v_cmp_gt_i32_e64 s[6:7], s80, v35
	v_mov_b32_dpp v36, v30 row_shr:1 row_mask:0xf bank_mask:0xf
	v_mov_b32_dpp v37, v26 row_shr:1 row_mask:0xf bank_mask:0xf
	v_mov_b32_dpp v39, v30 row_shr:2 row_mask:0xf bank_mask:0xf
	v_mov_b32_dpp v62, v26 row_shr:2 row_mask:0xf bank_mask:0xf
	v_mov_b32_dpp v38, v31 row_shr:1 row_mask:0xf bank_mask:0xf
	v_mov_b32_dpp v40, v27 row_shr:1 row_mask:0xf bank_mask:0xf
	v_mov_b32_dpp v54, v31 row_shr:2 row_mask:0xf bank_mask:0xf
	v_mov_b32_dpp v66, v27 row_shr:2 row_mask:0xf bank_mask:0xf
	v_mov_b32_dpp v41, v32 row_shr:1 row_mask:0xf bank_mask:0xf
	v_mov_b32_dpp v55, v28 row_shr:1 row_mask:0xf bank_mask:0xf
	v_mov_b32_dpp v63, v32 row_shr:2 row_mask:0xf bank_mask:0xf
	v_mov_b32_dpp v67, v28 row_shr:2 row_mask:0xf bank_mask:0xf
	v_mov_b32_dpp v56, v33 row_shr:1 row_mask:0xf bank_mask:0xf
	v_mov_b32_dpp v64, v29 row_shr:1 row_mask:0xf bank_mask:0xf
	v_mov_b32_dpp v68, v33 row_shr:2 row_mask:0xf bank_mask:0xf
	v_mov_b32_dpp v65, v29 row_shr:2 row_mask:0xf bank_mask:0xf
	s_and_b64 s[8:9], vcc, s[6:7]
	s_and_saveexec_b64 s[6:7], s[8:9]
	s_cbranch_execz .LBB0_108
	v_and_b32_e32 v57, 0x1fff, v35
	v_cmp_gt_u32_e32 vcc, 2, v57
	v_pk_mul_f32 v[22:23], v[22:23], v[34:35] op_sel_hi:[1,0]
	v_pk_mul_f32 v[24:25], v[24:25], v[34:35] op_sel_hi:[1,0]
	v_cndmask_b32_e64 v87, v66, 0, vcc
	v_cndmask_b32_e64 v86, v62, 0, vcc
	v_cndmask_b32_e64 v89, v65, 0, vcc
	v_cndmask_b32_e64 v88, v67, 0, vcc
	v_cndmask_b32_e64 v67, v54, 0, vcc
	v_cndmask_b32_e64 v66, v39, 0, vcc
	v_cndmask_b32_e64 v69, v68, 0, vcc
	v_cndmask_b32_e64 v68, v63, 0, vcc
	v_cmp_eq_u32_e32 vcc, 0, v57
	v_pk_mul_f32 v[14:15], v[14:15], v[34:35] op_sel_hi:[1,0]
	v_pk_mul_f32 v[16:17], v[16:17], v[34:35] op_sel_hi:[1,0]
	v_cndmask_b32_e64 v62, v55, 0, vcc
	v_cndmask_b32_e64 v55, v40, 0, vcc
	v_cndmask_b32_e64 v54, v37, 0, vcc
	v_cndmask_b32_e64 v57, v56, 0, vcc
	v_cndmask_b32_e64 v56, v41, 0, vcc
	s_waitcnt vmcnt(1)
	v_pk_fma_f32 v[40:41], v[78:79], v[86:87], v[82:83]
	v_cndmask_b32_e64 v63, v64, 0, vcc
	v_pk_fma_f32 v[40:41], v[74:75], v[54:55], v[40:41]
	v_cndmask_b32_e64 v37, v38, 0, vcc
	v_pk_fma_f32 v[40:41], v[26:27], v[70:71], v[40:41]
	v_pk_fma_f32 v[38:39], v[80:81], v[88:89], v[84:85]
	v_mul_f32_e32 v54, 0xbfb8aa3b, v40
	v_mul_f32_e32 v55, 0xbfb8aa3b, v41
	v_exp_f32_e32 v54, v54
	v_exp_f32_e32 v55, v55
	v_pk_fma_f32 v[38:39], v[76:77], v[62:63], v[38:39]
	v_cndmask_b32_e64 v36, v36, 0, vcc
	v_add_f32_e32 v54, 1.0, v54
	v_add_f32_e32 v55, 1.0, v55
	v_rcp_f32_e32 v54, v54
	v_rcp_f32_e32 v55, v55
	v_pk_fma_f32 v[38:39], v[28:29], v[72:73], v[38:39]
	v_pk_mul_f32 v[40:41], v[40:41], v[54:55]
	s_nop 0
	v_pk_mul_f32 v[22:23], v[22:23], v[40:41]
	v_mul_f32_e32 v40, 0xbfb8aa3b, v38
	v_mul_f32_e32 v41, 0xbfb8aa3b, v39
	v_exp_f32_e32 v40, v40
	v_exp_f32_e32 v41, v41
	v_add_f32_e32 v40, 1.0, v40
	v_add_f32_e32 v41, 1.0, v41
	v_rcp_f32_e32 v40, v40
	v_rcp_f32_e32 v41, v41
	s_nop 0
	v_pk_mul_f32 v[38:39], v[38:39], v[40:41]
	s_waitcnt vmcnt(0)
	v_pk_fma_f32 v[40:41], v[50:51], v[66:67], v[58:59]
	v_pk_mul_f32 v[24:25], v[24:25], v[38:39]
	v_pk_fma_f32 v[36:37], v[46:47], v[36:37], v[40:41]
	v_pk_fma_f32 v[38:39], v[52:53], v[68:69], v[60:61]
	v_pk_fma_f32 v[36:37], v[30:31], v[42:43], v[36:37]
	v_pk_fma_f32 v[38:39], v[48:49], v[56:57], v[38:39]
	v_mul_f32_e32 v40, 0xbfb8aa3b, v36
	v_mul_f32_e32 v41, 0xbfb8aa3b, v37
	v_exp_f32_e32 v40, v40
	v_exp_f32_e32 v41, v41
	v_pk_fma_f32 v[38:39], v[32:33], v[44:45], v[38:39]
	v_add_f32_e32 v40, 1.0, v40
	v_add_f32_e32 v41, 1.0, v41
	v_rcp_f32_e32 v40, v40
	v_rcp_f32_e32 v41, v41
	s_nop 0
	v_pk_mul_f32 v[36:37], v[36:37], v[40:41]
	s_nop 0
	v_pk_mul_f32 v[14:15], v[14:15], v[36:37]
	v_mul_f32_e32 v36, 0xbfb8aa3b, v38
	v_mul_f32_e32 v37, 0xbfb8aa3b, v39
	v_exp_f32_e32 v36, v36
	v_exp_f32_e32 v37, v37
	v_cvt_pk_bf16_f32 v14, v14, v15
	v_add_f32_e32 v36, 1.0, v36
	v_add_f32_e32 v37, 1.0, v37
	v_rcp_f32_e32 v36, v36
	v_rcp_f32_e32 v37, v37
	s_nop 0
	v_pk_mul_f32 v[36:37], v[38:39], v[36:37]
	s_nop 0
	v_pk_mul_f32 v[16:17], v[16:17], v[36:37]
	s_nop 0
	v_cvt_pk_bf16_f32 v15, v16, v17
	v_cvt_pk_bf16_f32 v16, v22, v23
	v_mov_b64_e32 v[22:23], s[16:17]
	v_mad_i64_i32 v[22:23], s[8:9], v35, s58, v[22:23]
	v_cvt_pk_bf16_f32 v17, v24, v25
	v_lshl_add_u64 v[22:23], v[226:227], 1, v[22:23]
	global_store_dwordx4 v[22:23], v[14:17], off
.LBB0_108:
	s_or_b64 exec, exec, s[6:7]
	s_nop 0
	v_pk_mul_f32 v[14:15], v[20:21], v[224:225] op_sel_hi:[1,0]
	v_mov_b32_dpp v21, v31 row_ror:1 row_mask:0xf bank_mask:0xf
	v_mov_b32_dpp v22, v31 row_ror:2 row_mask:0xf bank_mask:0xf
	v_mov_b32_dpp v35, v27 row_ror:1 row_mask:0xf bank_mask:0xf
	v_mov_b32_dpp v31, v27 row_ror:2 row_mask:0xf bank_mask:0xf
	v_pk_mul_f32 v[16:17], v[18:19], v[224:225] op_sel_hi:[1,0]
	v_mov_b32_dpp v24, v32 row_ror:1 row_mask:0xf bank_mask:0xf
	v_mov_b32_dpp v36, v28 row_ror:1 row_mask:0xf bank_mask:0xf
	v_mov_b32_dpp v23, v32 row_ror:2 row_mask:0xf bank_mask:0xf
	v_mov_b32_dpp v27, v28 row_ror:2 row_mask:0xf bank_mask:0xf
	v_mov_b32_dpp v19, v30 row_ror:1 row_mask:0xf bank_mask:0xf
	v_mov_b32_dpp v20, v30 row_ror:2 row_mask:0xf bank_mask:0xf
	v_mov_b32_dpp v32, v29 row_ror:1 row_mask:0xf bank_mask:0xf
	v_mov_b32_dpp v28, v29 row_ror:2 row_mask:0xf bank_mask:0xf
	v_add_u32_e32 v29, 0xb0, v183
	v_mov_b32_dpp v34, v26 row_ror:1 row_mask:0xf bank_mask:0xf
	v_mov_b32_dpp v30, v26 row_ror:2 row_mask:0xf bank_mask:0xf
	v_add_u32_e32 v18, s48, v29
	v_pk_mul_f32 v[12:13], v[12:13], v[224:225] op_sel_hi:[1,0]
	v_pk_mul_f32 v[10:11], v[10:11], v[224:225] op_sel_hi:[1,0]
	v_mov_b32_dpp v26, v33 row_ror:1 row_mask:0xf bank_mask:0xf
	v_mov_b32_dpp v25, v33 row_ror:2 row_mask:0xf bank_mask:0xf
	v_cmp_lt_i32_e32 vcc, 1, v29
	v_cmp_gt_i32_e64 s[6:7], s80, v18
	v_mov_b32_dpp v19, v16 row_shr:1 row_mask:0xf bank_mask:0xf
	v_mov_b32_dpp v34, v10 row_shr:1 row_mask:0xf bank_mask:0xf
	v_mov_b32_dpp v20, v16 row_shr:2 row_mask:0xf bank_mask:0xf
	v_mov_b32_dpp v30, v10 row_shr:2 row_mask:0xf bank_mask:0xf
	v_mov_b32_dpp v21, v17 row_shr:1 row_mask:0xf bank_mask:0xf
	v_mov_b32_dpp v35, v11 row_shr:1 row_mask:0xf bank_mask:0xf
	v_mov_b32_dpp v22, v17 row_shr:2 row_mask:0xf bank_mask:0xf
	v_mov_b32_dpp v31, v11 row_shr:2 row_mask:0xf bank_mask:0xf
	v_mov_b32_dpp v24, v14 row_shr:1 row_mask:0xf bank_mask:0xf
	v_mov_b32_dpp v36, v12 row_shr:1 row_mask:0xf bank_mask:0xf
	v_mov_b32_dpp v23, v14 row_shr:2 row_mask:0xf bank_mask:0xf
	v_mov_b32_dpp v27, v12 row_shr:2 row_mask:0xf bank_mask:0xf
	v_mov_b32_dpp v26, v15 row_shr:1 row_mask:0xf bank_mask:0xf
	v_mov_b32_dpp v32, v13 row_shr:1 row_mask:0xf bank_mask:0xf
	v_mov_b32_dpp v25, v15 row_shr:2 row_mask:0xf bank_mask:0xf
	v_mov_b32_dpp v28, v13 row_shr:2 row_mask:0xf bank_mask:0xf
	s_and_b64 s[6:7], vcc, s[6:7]
	s_and_saveexec_b64 s[8:9], s[6:7]
	s_cbranch_execz .LBB0_110
	v_and_b32_e32 v29, 0x1fff, v18
	v_cmp_gt_u32_e64 s[6:7], 2, v29
	v_cmp_eq_u32_e32 vcc, 0, v29
	v_pk_mul_f32 v[6:7], v[6:7], v[224:225] op_sel_hi:[1,0]
	v_cndmask_b32_e64 v31, v31, 0, s[6:7]
	v_cndmask_b32_e64 v30, v30, 0, s[6:7]
	v_cndmask_b32_e64 v35, v35, 0, vcc
	v_cndmask_b32_e64 v34, v34, 0, vcc
	s_waitcnt vmcnt(1)
	v_pk_fma_f32 v[30:31], v[78:79], v[30:31], v[82:83]
	v_cndmask_b32_e64 v29, v28, 0, s[6:7]
	v_pk_fma_f32 v[30:31], v[74:75], v[34:35], v[30:31]
	v_cndmask_b32_e64 v28, v27, 0, s[6:7]
	v_pk_fma_f32 v[10:11], v[10:11], v[70:71], v[30:31]
	v_cndmask_b32_e64 v33, v32, 0, vcc
	v_mul_f32_e32 v27, 0xbfb8aa3b, v10
	v_exp_f32_e32 v27, v27
	v_mul_f32_e32 v30, 0xbfb8aa3b, v11
	v_exp_f32_e32 v30, v30
	v_cndmask_b32_e64 v32, v36, 0, vcc
	v_pk_fma_f32 v[28:29], v[80:81], v[28:29], v[84:85]
	v_add_f32_e32 v27, 1.0, v27
	v_pk_fma_f32 v[28:29], v[76:77], v[32:33], v[28:29]
	v_cndmask_b32_e64 v20, v20, 0, s[6:7]
	v_pk_fma_f32 v[12:13], v[12:13], v[72:73], v[28:29]
	v_rcp_f32_e32 v28, v27
	v_add_f32_e32 v27, 1.0, v30
	v_rcp_f32_e32 v29, v27
	v_mul_f32_e32 v27, 0xbfb8aa3b, v12
	v_exp_f32_e32 v27, v27
	v_mul_f32_e32 v30, 0xbfb8aa3b, v13
	v_exp_f32_e32 v31, v30
	v_pk_mul_f32 v[10:11], v[10:11], v[28:29]
	v_add_f32_e32 v27, 1.0, v27
	v_rcp_f32_e32 v30, v27
	v_add_f32_e32 v27, 1.0, v31
	v_rcp_f32_e32 v31, v27
	v_pk_mul_f32 v[6:7], v[6:7], v[10:11]
	v_pk_mul_f32 v[8:9], v[8:9], v[224:225] op_sel_hi:[1,0]
	v_cndmask_b32_e64 v25, v25, 0, s[6:7]
	v_pk_mul_f32 v[10:11], v[12:13], v[30:31]
	v_cndmask_b32_e64 v13, v21, 0, vcc
	v_cndmask_b32_e64 v21, v22, 0, s[6:7]
	v_cndmask_b32_e64 v12, v19, 0, vcc
	s_waitcnt vmcnt(0)
	v_pk_fma_f32 v[20:21], v[50:51], v[20:21], v[58:59]
	v_pk_mul_f32 v[8:9], v[8:9], v[10:11]
	v_pk_fma_f32 v[12:13], v[46:47], v[12:13], v[20:21]
	v_cndmask_b32_e64 v10, v24, 0, vcc
	v_pk_fma_f32 v[12:13], v[16:17], v[42:43], v[12:13]
	v_cndmask_b32_e64 v24, v23, 0, s[6:7]
	v_mul_f32_e32 v16, 0xbfb8aa3b, v12
	v_mul_f32_e32 v17, 0xbfb8aa3b, v13
	v_exp_f32_e32 v16, v16
	v_exp_f32_e32 v17, v17
	v_cndmask_b32_e64 v11, v26, 0, vcc
	v_pk_fma_f32 v[22:23], v[52:53], v[24:25], v[60:61]
	v_pk_mul_f32 v[2:3], v[2:3], v[224:225] op_sel_hi:[1,0]
	v_pk_fma_f32 v[10:11], v[48:49], v[10:11], v[22:23]
	v_pk_mul_f32 v[4:5], v[4:5], v[224:225] op_sel_hi:[1,0]
	v_pk_fma_f32 v[10:11], v[14:15], v[44:45], v[10:11]
	v_add_f32_e32 v14, 1.0, v16
	v_add_f32_e32 v15, 1.0, v17
	v_mul_f32_e32 v16, 0xbfb8aa3b, v10
	v_mul_f32_e32 v17, 0xbfb8aa3b, v11
	v_exp_f32_e32 v16, v16
	v_exp_f32_e32 v17, v17
	v_rcp_f32_e32 v14, v14
	v_rcp_f32_e32 v15, v15
	v_add_f32_e32 v16, 1.0, v16
	v_add_f32_e32 v17, 1.0, v17
	v_rcp_f32_e32 v16, v16
	v_rcp_f32_e32 v17, v17
	v_pk_mul_f32 v[12:13], v[12:13], v[14:15]
	v_pk_mul_f32 v[10:11], v[10:11], v[16:17]
	v_pk_mul_f32 v[2:3], v[2:3], v[12:13]
	v_pk_mul_f32 v[4:5], v[4:5], v[10:11]
	v_cvt_pk_bf16_f32 v2, v2, v3
	v_cvt_pk_bf16_f32 v3, v4, v5
	v_cvt_pk_bf16_f32 v4, v6, v7
	v_mov_b64_e32 v[6:7], s[16:17]
	v_mad_i64_i32 v[6:7], s[6:7], v18, s58, v[6:7]
	v_cvt_pk_bf16_f32 v5, v8, v9
	v_lshl_add_u64 v[6:7], v[226:227], 1, v[6:7]
	global_store_dwordx4 v[6:7], v[2:5], off
